# q_lat operand loads hoisted behind the scoring barrier; merge results transposed via LDS for coalesced o_lat stores
# speedup vs baseline: 1.0517x; 1.0024x over previous
.LBB0_439:
	s_add_i32 s36, s81, 1
	s_lshr_b32 s36, s36, 1
	v_mov_b32_e32 v0, s81
	v_mov_b32_e32 v1, s36
	s_lshl_b32 s36, s36, 2
	v_or_b32_e32 v160, s38, v185
	v_cndmask_b32_e64 v0, v0, v1, s[40:41]
	v_mov_b32_e32 v1, s36
	v_cmp_lt_i32_e32 vcc, s16, v160
	v_mov_b32_e32 v3, 0
	v_cndmask_b32_e64 v5, v1, 0, s[40:41]
	v_lshlrev_b32_e32 v6, 2, v0
	s_mov_b64 s[42:43], -1
	v_lshlrev_b32_e32 v162, 2, v172
	v_mov_b32_e32 v4, 0
	s_waitcnt lgkmcnt(0)
	s_barrier
	v_readlane_b32 s100, v250, 48
	v_readlane_b32 s101, v250, 49
	v_and_b32_e32 v243, 15, v172
	v_lshrrev_b32_e32 v244, 4, v172
	v_lshlrev_b32_e32 v243, 9, v243
	v_lshl_add_u32 v243, v244, 4, v243
	v_lshl_add_u32 v243, v160, 13, v243
	s_nop 1
	global_load_dwordx4 v[64:67], v243, s[100:101]
	global_load_dwordx4 v[68:71], v243, s[100:101] offset:64
	global_load_dwordx4 v[72:75], v243, s[100:101] offset:128
	global_load_dwordx4 v[76:79], v243, s[100:101] offset:192
	global_load_dwordx4 v[80:83], v243, s[100:101] offset:256
	global_load_dwordx4 v[84:87], v243, s[100:101] offset:320
	global_load_dwordx4 v[88:91], v243, s[100:101] offset:384
	global_load_dwordx4 v[92:95], v243, s[100:101] offset:448
	s_and_saveexec_b64 s[38:39], vcc
	s_cbranch_execz .LBB0_441
	v_lshl_add_u32 v0, v172, 6, v187
	ds_read_b128 v[8:11], v0
	ds_read_b128 v[12:15], v0 offset:16
	s_waitcnt vmcnt(31)
	ds_read_b128 v[16:19], v0 offset:32
	s_waitcnt vmcnt(30)
	ds_read_b128 v[20:23], v0 offset:48
	s_waitcnt vmcnt(10)
	v_add_u32_e32 v35, 4, v162
	s_waitcnt lgkmcnt(3)
	v_add_u32_sdwa v0, v8, v8 dst_sel:DWORD dst_unused:UNUSED_PAD src0_sel:WORD_1 src1_sel:WORD_0
	v_and_b32_e32 v1, 0xffff, v9
	v_lshrrev_b32_e32 v2, 16, v9
	v_add3_u32 v0, v2, v0, v1
	v_and_b32_e32 v4, 0xffff, v10
	v_lshrrev_b32_e32 v7, 16, v10
	v_add3_u32 v0, v7, v0, v4
	v_and_b32_e32 v9, 0xffff, v11
	v_lshrrev_b32_e32 v10, 16, v11
	v_add3_u32 v0, v10, v0, v9
	s_waitcnt lgkmcnt(2)
	v_and_b32_e32 v11, 0xffff, v12
	v_lshrrev_b32_e32 v12, 16, v12
	v_add3_u32 v0, v12, v0, v11
	v_and_b32_e32 v24, 0xffff, v13
	v_lshrrev_b32_e32 v13, 16, v13
	v_add3_u32 v0, v13, v0, v24
	v_and_b32_e32 v25, 0xffff, v14
	v_lshrrev_b32_e32 v14, 16, v14
	v_add3_u32 v0, v14, v0, v25
	v_and_b32_e32 v26, 0xffff, v15
	v_lshrrev_b32_e32 v15, 16, v15
	v_add3_u32 v0, v15, v0, v26
	s_waitcnt lgkmcnt(1)
	v_and_b32_e32 v27, 0xffff, v16
	v_lshrrev_b32_e32 v16, 16, v16
	v_add3_u32 v0, v16, v0, v27
	v_and_b32_e32 v28, 0xffff, v17
	v_lshrrev_b32_e32 v17, 16, v17
	v_add3_u32 v0, v17, v0, v28
	v_and_b32_e32 v29, 0xffff, v18
	v_lshrrev_b32_e32 v18, 16, v18
	v_add3_u32 v0, v18, v0, v29
	v_and_b32_e32 v30, 0xffff, v19
	v_lshrrev_b32_e32 v19, 16, v19
	v_add3_u32 v0, v19, v0, v30
	s_waitcnt lgkmcnt(0)
	v_and_b32_e32 v31, 0xffff, v20
	v_lshrrev_b32_e32 v20, 16, v20
	v_add3_u32 v0, v20, v0, v31
	v_and_b32_e32 v32, 0xffff, v21
	v_lshrrev_b32_e32 v21, 16, v21
	v_add3_u32 v0, v21, v0, v32
	v_and_b32_e32 v33, 0xffff, v22
	v_lshrrev_b32_e32 v22, 16, v22
	v_add3_u32 v0, v22, v0, v33
	v_and_b32_e32 v34, 0xffff, v23
	v_lshrrev_b32_e32 v23, 16, v23
	v_add3_u32 v0, v23, v0, v34
	v_and_b32_e32 v35, 0xfc, v35
	ds_bpermute_b32 v35, v35, v0
	v_cmp_gt_i32_e64 s[44:45], 63, v172
	v_add_u32_e32 v36, 8, v162
	v_and_b32_e32 v36, 0xfc, v36
	s_movk_i32 s15, 0x80
	s_waitcnt lgkmcnt(0)
	v_cndmask_b32_e64 v35, 0, v35, s[44:45]
	v_add_u32_e32 v35, v35, v0
	ds_bpermute_b32 v36, v36, v35
	v_cmp_gt_i32_e64 s[44:45], 62, v172
	v_cmp_gt_i32_e64 s[46:47], 32, v172
	s_movk_i32 s16, 0x100
	s_waitcnt lgkmcnt(0)
	v_cndmask_b32_e64 v36, 0, v36, s[44:45]
	v_add_u32_e32 v35, v36, v35
	v_add_u32_e32 v36, 16, v162
	v_and_b32_e32 v36, 0xfc, v36
	ds_bpermute_b32 v36, v36, v35
	v_cmp_gt_i32_e64 s[44:45], 60, v172
	s_waitcnt lgkmcnt(0)
	s_nop 0
	v_cndmask_b32_e64 v36, 0, v36, s[44:45]
	v_add_u32_e32 v35, v36, v35
	v_add_u32_e32 v36, 32, v162
	v_and_b32_e32 v36, 0xfc, v36
	ds_bpermute_b32 v36, v36, v35
	v_cmp_gt_i32_e64 s[44:45], 56, v172
	s_waitcnt lgkmcnt(0)
	s_nop 0
	v_cndmask_b32_e64 v36, 0, v36, s[44:45]
	v_add_u32_e32 v35, v36, v35
	v_add_u32_e32 v36, 64, v162
	v_and_b32_e32 v36, 0xfc, v36
	ds_bpermute_b32 v36, v36, v35
	v_cmp_gt_i32_e64 s[44:45], 48, v172
	s_waitcnt lgkmcnt(0)
	s_nop 0
	v_cndmask_b32_e64 v36, 0, v36, s[44:45]
	v_add_u32_e32 v35, v36, v35
	v_bitop3_b32 v36, v162, s15, v182 bitop3:0x6c
	ds_bpermute_b32 v36, v36, v35
	s_movk_i32 s15, 0xff
	v_cmp_ge_u32_e64 s[44:45], v5, v6
	s_waitcnt lgkmcnt(0)
	v_cndmask_b32_e64 v36, 0, v36, s[46:47]
	v_add_u32_e32 v35, v36, v35
	v_sub_u32_e32 v0, v35, v0
	v_add_u32_e32 v0, v23, v0
	v_cmp_lt_i32_e64 s[46:47], s15, v35
	v_add_u32_e32 v23, v34, v0
	s_bcnt1_i32_b64 s42, s[46:47]
	v_cmp_lt_i32_e64 s[46:47], s15, v23
	v_add_u32_e32 v22, v22, v23
	s_add_i32 s42, s42, -1
	v_cndmask_b32_e64 v34, -1, 30, s[46:47]
	v_cmp_gt_i32_e64 s[46:47], s16, v0
	s_movk_i32 s16, 0xff
	s_nop 0
	v_cndmask_b32_e64 v0, 31, v34, s[46:47]
	v_cmp_lt_i32_e64 s[46:47], s15, v22
	v_cmp_gt_i32_e64 s[48:49], 0, v0
	s_and_b64 s[36:37], s[46:47], s[48:49]
	v_cndmask_b32_e64 v0, v0, 29, s[36:37]
	v_add_u32_e32 v22, v33, v22
	v_cmp_lt_i32_e64 s[46:47], s15, v22
	v_cmp_gt_i32_e64 s[48:49], 0, v0
	s_and_b64 s[36:37], s[46:47], s[48:49]
	v_cndmask_b32_e64 v0, v0, 28, s[36:37]
	v_add_u32_e32 v21, v21, v22
	v_cmp_lt_i32_e64 s[46:47], s15, v21
	v_cmp_gt_i32_e64 s[48:49], 0, v0
	s_and_b64 s[36:37], s[46:47], s[48:49]
	v_cndmask_b32_e64 v0, v0, 27, s[36:37]
	v_add_u32_e32 v21, v32, v21
	v_cmp_lt_i32_e64 s[46:47], s15, v21
	v_cmp_gt_i32_e64 s[48:49], 0, v0
	s_and_b64 s[36:37], s[46:47], s[48:49]
	v_cndmask_b32_e64 v0, v0, 26, s[36:37]
	v_add_u32_e32 v20, v20, v21
	v_cmp_lt_i32_e64 s[46:47], s15, v20
	v_cmp_gt_i32_e64 s[48:49], 0, v0
	s_and_b64 s[36:37], s[46:47], s[48:49]
	v_cndmask_b32_e64 v0, v0, 25, s[36:37]
	v_add_u32_e32 v20, v31, v20
	v_cmp_lt_i32_e64 s[46:47], s15, v20
	v_cmp_gt_i32_e64 s[48:49], 0, v0
	s_and_b64 s[36:37], s[46:47], s[48:49]
	v_cndmask_b32_e64 v0, v0, 24, s[36:37]
	v_add_u32_e32 v19, v19, v20
	v_cmp_lt_i32_e64 s[46:47], s15, v19
	v_cmp_gt_i32_e64 s[48:49], 0, v0
	s_and_b64 s[36:37], s[46:47], s[48:49]
	v_cndmask_b32_e64 v0, v0, 23, s[36:37]
	v_add_u32_e32 v19, v30, v19
	v_cmp_lt_i32_e64 s[46:47], s15, v19
	v_cmp_gt_i32_e64 s[48:49], 0, v0
	s_and_b64 s[36:37], s[46:47], s[48:49]
	v_cndmask_b32_e64 v0, v0, 22, s[36:37]
	v_add_u32_e32 v18, v18, v19
	v_cmp_lt_i32_e64 s[46:47], s15, v18
	v_cmp_gt_i32_e64 s[48:49], 0, v0
	s_and_b64 s[36:37], s[46:47], s[48:49]
	v_cndmask_b32_e64 v0, v0, 21, s[36:37]
	v_add_u32_e32 v18, v29, v18
	v_cmp_lt_i32_e64 s[46:47], s15, v18
	v_cmp_gt_i32_e64 s[48:49], 0, v0
	s_and_b64 s[36:37], s[46:47], s[48:49]
	v_cndmask_b32_e64 v0, v0, 20, s[36:37]
	v_add_u32_e32 v17, v17, v18
	v_cmp_lt_i32_e64 s[46:47], s15, v17
	v_cmp_gt_i32_e64 s[48:49], 0, v0
	s_and_b64 s[36:37], s[46:47], s[48:49]
	v_cndmask_b32_e64 v0, v0, 19, s[36:37]
	v_add_u32_e32 v17, v28, v17
	v_cmp_lt_i32_e64 s[46:47], s15, v17
	v_cmp_gt_i32_e64 s[48:49], 0, v0
	s_and_b64 s[36:37], s[46:47], s[48:49]
	v_cndmask_b32_e64 v0, v0, 18, s[36:37]
	v_add_u32_e32 v16, v16, v17
	v_cmp_lt_i32_e64 s[46:47], s15, v16
	v_cmp_gt_i32_e64 s[48:49], 0, v0
	s_and_b64 s[36:37], s[46:47], s[48:49]
	v_cndmask_b32_e64 v0, v0, 17, s[36:37]
	v_add_u32_e32 v16, v27, v16
	v_cmp_lt_i32_e64 s[46:47], s15, v16
	v_cmp_gt_i32_e64 s[48:49], 0, v0
	s_and_b64 s[36:37], s[46:47], s[48:49]
	v_cndmask_b32_e64 v0, v0, 16, s[36:37]
	v_add_u32_e32 v15, v15, v16
	v_cmp_lt_i32_e64 s[46:47], s15, v15
	v_cmp_gt_i32_e64 s[48:49], 0, v0
	s_and_b64 s[36:37], s[46:47], s[48:49]
	v_cndmask_b32_e64 v0, v0, 15, s[36:37]
	v_add_u32_e32 v15, v26, v15
	v_cmp_lt_i32_e64 s[46:47], s15, v15
	v_cmp_gt_i32_e64 s[48:49], 0, v0
	s_and_b64 s[36:37], s[46:47], s[48:49]
	v_cndmask_b32_e64 v0, v0, 14, s[36:37]
	v_add_u32_e32 v14, v14, v15
	v_cmp_lt_i32_e64 s[46:47], s15, v14
	v_cmp_gt_i32_e64 s[48:49], 0, v0
	s_and_b64 s[36:37], s[46:47], s[48:49]
	v_cndmask_b32_e64 v0, v0, 13, s[36:37]
	v_add_u32_e32 v14, v25, v14
	v_cmp_lt_i32_e64 s[46:47], s15, v14
	v_cmp_gt_i32_e64 s[48:49], 0, v0
	s_and_b64 s[36:37], s[46:47], s[48:49]
	v_cndmask_b32_e64 v0, v0, 12, s[36:37]
	v_add_u32_e32 v13, v13, v14
	v_cmp_lt_i32_e64 s[46:47], s15, v13
	v_cmp_gt_i32_e64 s[48:49], 0, v0
	s_and_b64 s[36:37], s[46:47], s[48:49]
	v_cndmask_b32_e64 v0, v0, 11, s[36:37]
	v_add_u32_e32 v13, v24, v13
	v_cmp_lt_i32_e64 s[46:47], s15, v13
	v_cmp_gt_i32_e64 s[48:49], 0, v0
	s_and_b64 s[36:37], s[46:47], s[48:49]
	v_cndmask_b32_e64 v0, v0, 10, s[36:37]
	v_add_u32_e32 v12, v12, v13
	v_cmp_lt_i32_e64 s[46:47], s15, v12
	v_cmp_gt_i32_e64 s[48:49], 0, v0
	s_and_b64 s[36:37], s[46:47], s[48:49]
	v_cndmask_b32_e64 v0, v0, 9, s[36:37]
	v_add_u32_e32 v11, v11, v12
	v_cmp_lt_i32_e64 s[46:47], s15, v11
	v_cmp_gt_i32_e64 s[48:49], 0, v0
	s_and_b64 s[36:37], s[46:47], s[48:49]
	v_cndmask_b32_e64 v0, v0, 8, s[36:37]
	v_add_u32_e32 v10, v10, v11
	v_cmp_lt_i32_e64 s[46:47], s15, v10
	v_cmp_gt_i32_e64 s[48:49], 0, v0
	s_and_b64 s[36:37], s[46:47], s[48:49]
	v_cndmask_b32_e64 v0, v0, 7, s[36:37]
	v_add_u32_e32 v9, v9, v10
	v_cmp_lt_i32_e64 s[46:47], s15, v9
	v_cmp_gt_i32_e64 s[48:49], 0, v0
	s_and_b64 s[36:37], s[46:47], s[48:49]
	v_cndmask_b32_e64 v0, v0, 6, s[36:37]
	v_add_u32_e32 v7, v7, v9
	v_cmp_lt_i32_e64 s[46:47], s15, v7
	v_cmp_gt_i32_e64 s[48:49], 0, v0
	s_and_b64 s[36:37], s[46:47], s[48:49]
	v_cndmask_b32_e64 v0, v0, 5, s[36:37]
	v_add_u32_e32 v4, v4, v7
	v_cmp_lt_i32_e64 s[46:47], s15, v4
	v_cmp_gt_i32_e64 s[48:49], 0, v0
	s_and_b64 s[36:37], s[46:47], s[48:49]
	v_cndmask_b32_e64 v0, v0, 4, s[36:37]
	v_add_u32_e32 v2, v2, v4
	v_cmp_lt_i32_e64 s[46:47], s15, v2
	v_cmp_gt_i32_e64 s[48:49], 0, v0
	s_and_b64 s[36:37], s[46:47], s[48:49]
	v_cndmask_b32_e64 v0, v0, 3, s[36:37]
	v_add_u32_e32 v1, v1, v2
	v_cmp_lt_i32_e64 s[46:47], s15, v1
	v_cmp_gt_i32_e64 s[48:49], 0, v0
	s_and_b64 s[36:37], s[46:47], s[48:49]
	v_cndmask_b32_e64 v0, v0, 2, s[36:37]
	v_add_u32_sdwa v1, v8, v1 dst_sel:DWORD dst_unused:UNUSED_PAD src0_sel:WORD_1 src1_sel:DWORD
	v_cmp_lt_i32_e64 s[46:47], s15, v1
	v_cmp_gt_i32_e64 s[48:49], 0, v0
	s_and_b64 s[36:37], s[46:47], s[48:49]
	v_cndmask_b32_e64 v0, v0, 1, s[36:37]
	v_add_u32_sdwa v1, v8, v1 dst_sel:DWORD dst_unused:UNUSED_PAD src0_sel:WORD_0 src1_sel:DWORD
	v_max_i32_e32 v2, 0, v0
	v_cmp_lt_i32_e64 s[46:47], s15, v1
	s_lshl_b32 s37, s42, 26
	s_nop 0
	v_cndmask_b32_e64 v0, v0, v2, s[46:47]
	s_nop 0
	v_readlane_b32 s36, v0, s42
	s_lshl_b32 s36, s36, 21
	s_add_i32 s36, s36, s37
	v_mov_b32_e32 v4, s36
	s_orn2_b64 s[42:43], s[44:45], exec

.LBB0_507:
	s_or_b64 exec, exec, s[38:39]
	v_add_u32_e32 v0, v172, v192
	v_lshl_add_u32 v0, v0, 5, 0
	v_add_u32_e32 v4, 0x23000, v0
	v_mov_b32_e32 v0, v169
	s_waitcnt lgkmcnt(0)
	s_barrier
	v_min_i32_e32 v173, 0xff, v160
	v_mov_b32_e32 v1, v0
	v_mov_b32_e32 v2, v0
	v_mov_b32_e32 v3, v0
	ds_write_b128 v4, v[0:3]
	ds_write_b128 v4, v[0:3] offset:16
	v_add_u32_e32 v1, 32, v173
	v_lshrrev_b32_e32 v1, 5, v1
	v_add_u32_e32 v2, 1, v1
	v_and_b32_e32 v163, 15, v172
	v_lshrrev_b32_e32 v2, 1, v2
	v_ashrrev_i32_e32 v165, 4, v172
	v_mov_b32_e32 v161, v169
	v_lshlrev_b32_e32 v0, 8, v163
	v_cndmask_b32_e64 v197, v2, 0, s[40:41]
	v_cndmask_b32_e64 v177, v1, v2, s[40:41]
	v_mov_b32_e32 v3, 0
	v_lshlrev_b64 v[174:175], 12, v[160:161]
	v_lshlrev_b32_e32 v176, 2, v165
	v_cmp_lt_u32_e32 vcc, v197, v177
	v_mov_b32_e32 v204, 0xff800000
	v_lshlrev_b32_e32 v168, 1, v0
	v_mov_b32_e32 v2, v3
	v_mov_b32_e32 v1, v3
	v_mov_b32_e32 v0, v3
	v_mov_b32_e32 v7, v3
	v_mov_b32_e32 v6, v3
	v_mov_b32_e32 v5, v3
	v_mov_b32_e32 v4, v3
	v_mov_b32_e32 v11, v3
	v_mov_b32_e32 v10, v3
	v_mov_b32_e32 v9, v3
	v_mov_b32_e32 v8, v3
	v_mov_b32_e32 v15, v3
	v_mov_b32_e32 v14, v3
	v_mov_b32_e32 v13, v3
	v_mov_b32_e32 v12, v3
	s_waitcnt vmcnt(3)
	v_mov_b32_e32 v63, v3
	v_mov_b32_e32 v62, v3
	v_mov_b32_e32 v61, v3
	v_mov_b32_e32 v60, v3
	s_waitcnt vmcnt(2)
	v_mov_b32_e32 v59, v3
	v_mov_b32_e32 v58, v3
	v_mov_b32_e32 v57, v3
	v_mov_b32_e32 v56, v3
	s_waitcnt vmcnt(1)
	v_mov_b32_e32 v55, v3
	v_mov_b32_e32 v54, v3
	v_mov_b32_e32 v53, v3
	v_mov_b32_e32 v52, v3
	s_waitcnt vmcnt(0)
	v_mov_b32_e32 v51, v3
	v_mov_b32_e32 v50, v3
	v_mov_b32_e32 v49, v3
	v_mov_b32_e32 v48, v3
	v_mov_b32_e32 v47, v3
	v_mov_b32_e32 v46, v3
	v_mov_b32_e32 v45, v3
	v_mov_b32_e32 v44, v3
	v_mov_b32_e32 v43, v3
	v_mov_b32_e32 v42, v3
	v_mov_b32_e32 v41, v3
	v_mov_b32_e32 v40, v3
	v_mov_b32_e32 v39, v3
	v_mov_b32_e32 v38, v3
	v_mov_b32_e32 v37, v3
	v_mov_b32_e32 v36, v3
	v_mov_b32_e32 v35, v3
	v_mov_b32_e32 v34, v3
	v_mov_b32_e32 v33, v3
	v_mov_b32_e32 v32, v3
	v_mov_b32_e32 v31, v3
	v_mov_b32_e32 v30, v3
	v_mov_b32_e32 v29, v3
	v_mov_b32_e32 v28, v3
	v_mov_b32_e32 v27, v3
	v_mov_b32_e32 v26, v3
	v_mov_b32_e32 v25, v3
	v_mov_b32_e32 v24, v3
	v_mov_b32_e32 v23, v3
	v_mov_b32_e32 v22, v3
	v_mov_b32_e32 v21, v3
	v_mov_b32_e32 v20, v3
	v_mov_b32_e32 v19, v3
	v_mov_b32_e32 v18, v3
	v_mov_b32_e32 v17, v3
	v_mov_b32_e32 v16, v3
	v_mov_b32_e32 v164, v3
	s_and_saveexec_b64 s[0:1], vcc
	s_cbranch_execz .LBB0_513
	v_readlane_b32 s36, v250, 48
	v_readlane_b32 s37, v250, 49
	v_lshlrev_b32_e32 v2, 3, v165
	v_ashrrev_i32_e32 v3, 31, v2
	v_lshl_add_u64 v[0:1], v[174:175], 1, s[36:37]
	v_lshl_add_u64 v[0:1], v[0:1], 0, v[168:169]
	v_lshlrev_b64 v[2:3], 1, v[2:3]
	v_lshl_add_u32 v198, v163, 2, v186
	v_lshl_add_u64 v[0:1], v[0:1], 0, v[2:3]
	v_lshl_add_u32 v4, v197, 7, v198
	ds_read2_b32 v[4:5], v4 offset1:16
	v_readlane_b32 s36, v250, 44
	v_readlane_b32 s37, v250, 45
	v_mov_b32_e32 v205, 0
	s_mov_b32 s100, s36
	s_mov_b32 s101, s37
	v_and_b32_e32 v224, 31, v172
	v_lshlrev_b32_e32 v224, 4, v224
	v_lshrrev_b32_e32 v225, 5, v172
	v_mul_u32_u24_e32 v226, 0x2200, v225
	v_add3_u32 v226, v226, v224, v193
	v_lshl_add_u32 v225, v225, 6, v186
	v_lshl_add_u32 v227, v197, 7, v225
	v_mov_b32_e32 v228, 0xff800000
	ds_read_b128 v[234:237], v227
	ds_read_b128 v[238:241], v227 offset:16
	ds_read_b128 v[242:245], v227 offset:32
	ds_read_b128 v[246:249], v227 offset:48
	s_waitcnt lgkmcnt(0)
	v_lshl_add_u32 v234, v234, 9, v224
	v_lshl_add_u32 v235, v235, 9, v224
	v_lshl_add_u32 v236, v236, 9, v224
	v_lshl_add_u32 v237, v237, 9, v224
	v_lshl_add_u32 v238, v238, 9, v224
	v_lshl_add_u32 v239, v239, 9, v224
	v_lshl_add_u32 v240, v240, 9, v224
	v_lshl_add_u32 v241, v241, 9, v224
	v_lshl_add_u32 v242, v242, 9, v224
	v_lshl_add_u32 v243, v243, 9, v224
	v_lshl_add_u32 v244, v244, 9, v224
	v_lshl_add_u32 v245, v245, 9, v224
	v_lshl_add_u32 v246, v246, 9, v224
	v_lshl_add_u32 v247, v247, 9, v224
	v_lshl_add_u32 v248, v248, 9, v224
	v_lshl_add_u32 v249, v249, 9, v224
	global_load_dwordx4 v[96:99], v234, s[100:101]
	global_load_dwordx4 v[100:103], v235, s[100:101]
	global_load_dwordx4 v[104:107], v236, s[100:101]
	global_load_dwordx4 v[108:111], v237, s[100:101]
	global_load_dwordx4 v[112:115], v238, s[100:101]
	global_load_dwordx4 v[116:119], v239, s[100:101]
	global_load_dwordx4 v[120:123], v240, s[100:101]
	global_load_dwordx4 v[124:127], v241, s[100:101]
	global_load_dwordx4 v[128:131], v242, s[100:101]
	global_load_dwordx4 v[132:135], v243, s[100:101]
	global_load_dwordx4 v[136:139], v244, s[100:101]
	global_load_dwordx4 v[140:143], v245, s[100:101]
	global_load_dwordx4 v[144:147], v246, s[100:101]
	global_load_dwordx4 v[148:151], v247, s[100:101]
	global_load_dwordx4 v[152:155], v248, s[100:101]
	global_load_dwordx4 v[156:159], v249, s[100:101]
	v_lshrrev_b32_e32 v0, 2, v163
	v_or_b32_e32 v0, v176, v0
	s_movk_i32 s36, 0x110
	v_mul_lo_u32 v0, v0, s36
	v_and_or_b32 v0, v162, 12, v0
	v_lshl_add_u32 v200, v0, 1, v193
	v_lshl_add_u32 v0, v165, 4, v193
	v_mul_u32_u24_e32 v1, 0x220, v163
	v_cmp_gt_i32_e32 vcc, s16, v160
	v_xor_b32_e32 v199, 0x80, v162
	v_xor_b32_e32 v201, 64, v162
	v_lshl_add_u32 v202, v197, 5, v176
	v_mov_b32_e32 v206, 0xff800000
	s_mov_b64 s[38:39], 0
	v_add_u32_e32 v203, v0, v1
	v_mov_b32_e32 v16, 0
	v_mov_b32_e32 v17, v205
	v_mov_b32_e32 v18, v205
	v_mov_b32_e32 v19, v205
	v_mov_b32_e32 v20, 0
	v_mov_b32_e32 v21, v205
	v_mov_b32_e32 v22, v205
	v_mov_b32_e32 v23, v205
	v_mov_b32_e32 v24, 0
	v_mov_b32_e32 v25, v205
	v_mov_b32_e32 v26, v205
	v_mov_b32_e32 v27, v205
	v_mov_b32_e32 v28, 0
	v_mov_b32_e32 v29, v205
	v_mov_b32_e32 v30, v205
	v_mov_b32_e32 v31, v205
	v_mov_b32_e32 v32, 0
	v_mov_b32_e32 v33, v205
	v_mov_b32_e32 v34, v205
	v_mov_b32_e32 v35, v205
	v_mov_b32_e32 v36, 0
	v_mov_b32_e32 v37, v205
	v_mov_b32_e32 v38, v205
	v_mov_b32_e32 v39, v205
	v_mov_b32_e32 v40, 0
	v_mov_b32_e32 v41, v205
	v_mov_b32_e32 v42, v205
	v_mov_b32_e32 v43, v205
	v_mov_b32_e32 v44, 0
	v_mov_b32_e32 v45, v205
	v_mov_b32_e32 v46, v205
	v_mov_b32_e32 v47, v205
	v_mov_b32_e32 v48, 0
	v_mov_b32_e32 v49, v205
	v_mov_b32_e32 v50, v205
	v_mov_b32_e32 v51, v205
	v_mov_b32_e32 v52, 0
	v_mov_b32_e32 v53, v205
	v_mov_b32_e32 v54, v205
	v_mov_b32_e32 v55, v205
	v_mov_b32_e32 v56, 0
	v_mov_b32_e32 v57, v205
	v_mov_b32_e32 v58, v205
	v_mov_b32_e32 v59, v205
	v_mov_b32_e32 v60, 0
	v_mov_b32_e32 v61, v205
	v_mov_b32_e32 v62, v205
	v_mov_b32_e32 v63, v205
	v_mov_b32_e32 v12, 0
	v_mov_b32_e32 v13, v205
	v_mov_b32_e32 v14, v205
	v_mov_b32_e32 v15, v205
	v_mov_b32_e32 v8, 0
	v_mov_b32_e32 v9, v205
	v_mov_b32_e32 v10, v205
	v_mov_b32_e32 v11, v205
	v_mov_b32_e32 v4, 0
	v_mov_b32_e32 v5, v205
	v_mov_b32_e32 v6, v205
	v_mov_b32_e32 v7, v205
	v_mov_b32_e32 v0, 0
	v_mov_b32_e32 v1, v205
	v_mov_b32_e32 v2, v205
	v_mov_b32_e32 v3, v205
	s_branch .LBB0_510

.LBB0_515:
	s_or_b64 exec, exec, s[0:1]
	s_waitcnt lgkmcnt(0)
	s_barrier
	s_and_saveexec_b64 s[0:1], s[40:41]
	s_cbranch_execz .LBB0_517
	s_waitcnt vmcnt(0)
	v_lshl_add_u32 v67, v172, 2, v194
	ds_read2st64_b32 v[68:69], v67 offset1:1
	ds_read2st64_b32 v[96:97], v67 offset0:2 offset1:3
	ds_read2st64_b32 v[98:99], v67 offset0:4 offset1:5
	ds_read2st64_b32 v[100:101], v67 offset0:6 offset1:7
	ds_read2st64_b32 v[102:103], v67 offset0:8 offset1:9
	ds_read2st64_b32 v[104:105], v67 offset0:10 offset1:11
	ds_read2st64_b32 v[106:107], v67 offset0:12 offset1:13
	ds_read2st64_b32 v[108:109], v67 offset0:14 offset1:15
	ds_read2st64_b32 v[110:111], v67 offset0:16 offset1:17
	ds_read2st64_b32 v[112:113], v67 offset0:18 offset1:19
	ds_read2st64_b32 v[114:115], v67 offset0:20 offset1:21
	ds_read2st64_b32 v[116:117], v67 offset0:22 offset1:23
	ds_read2st64_b32 v[118:119], v67 offset0:24 offset1:25
	ds_read2st64_b32 v[120:121], v67 offset0:26 offset1:27
	ds_read2st64_b32 v[122:123], v67 offset0:28 offset1:29
	ds_read2st64_b32 v[124:125], v67 offset0:30 offset1:31
	ds_read2st64_b32 v[126:127], v67 offset0:32 offset1:33
	ds_read2st64_b32 v[128:129], v67 offset0:34 offset1:35
	ds_read2st64_b32 v[130:131], v67 offset0:36 offset1:37
	ds_read2st64_b32 v[132:133], v67 offset0:38 offset1:39
	ds_read2st64_b32 v[134:135], v67 offset0:40 offset1:41
	ds_read2st64_b32 v[136:137], v67 offset0:42 offset1:43
	ds_read2st64_b32 v[138:139], v67 offset0:44 offset1:45
	ds_read2st64_b32 v[140:141], v67 offset0:46 offset1:47
	ds_read2st64_b32 v[142:143], v67 offset0:48 offset1:49
	ds_read2st64_b32 v[144:145], v67 offset0:50 offset1:51
	ds_read2st64_b32 v[146:147], v67 offset0:52 offset1:53
	ds_read2st64_b32 v[148:149], v67 offset0:54 offset1:55
	ds_read2st64_b32 v[150:151], v67 offset0:56 offset1:57
	ds_read2st64_b32 v[152:153], v67 offset0:58 offset1:59
	ds_read2st64_b32 v[154:155], v67 offset0:60 offset1:61
	ds_read2st64_b32 v[156:157], v67 offset0:62 offset1:63
	ds_read2st64_b32 v[158:159], v67 offset0:64 offset1:65
	v_max_f32_e32 v70, v204, v204
	v_readlane_b32 s36, v250, 50
	v_readlane_b32 s37, v250, 51
	v_and_b32_e32 v75, 15, v172
	v_lshrrev_b32_e32 v76, 4, v172
	v_mul_u32_u24_e32 v75, 0x210, v75
	v_lshl_add_u32 v75, v76, 3, v75
	v_add_u32_e32 v75, v75, v193
	v_lshrrev_b32_e32 v76, 5, v172
	v_mul_u32_u24_e32 v76, 0x210, v76
	v_and_b32_e32 v77, 31, v172
	v_lshl_add_u32 v76, v77, 4, v76
	v_add_u32_e32 v76, v76, v193
	s_waitcnt lgkmcnt(0)
	v_max_f32_e32 v66, v68, v68
	v_max_f32_e32 v66, v70, v66
	v_sub_f32_e32 v70, v204, v66
	v_sub_f32_e32 v66, v68, v66
	v_exp_f32_e32 v70, v70
	v_exp_f32_e32 v71, v66
	v_mov_b32_e32 v165, v69
	v_lshl_add_u64 v[64:65], v[174:175], 1, s[36:37]
	v_lshlrev_b32_e32 v72, 4, v172
	v_mov_b32_e32 v73, 0
	v_pk_mul_f32 v[68:69], v[164:165], v[70:71]
	v_lshl_add_u64 v[64:65], v[64:65], 0, v[72:73]
	v_add_f32_e32 v66, v68, v69
	v_div_scale_f32 v68, s[36:37], v66, v66, 1.0
	v_rcp_f32_e32 v69, v68
	s_nop 0
	v_fma_f32 v72, -v68, v69, 1.0
	v_fmac_f32_e32 v69, v72, v69
	v_div_scale_f32 v72, vcc, 1.0, v66, 1.0
	v_mul_f32_e32 v73, v72, v69
	v_fma_f32 v74, -v68, v73, v72
	v_fmac_f32_e32 v73, v74, v69
	v_fma_f32 v68, -v68, v73, v72
	v_div_fmas_f32 v68, v68, v69, v73
	v_div_fixup_f32 v68, v68, v66, 1.0
	v_mul_f32_e32 v66, v70, v68
	v_mul_f32_e32 v68, v71, v68
	s_mov_b64 s[36:37], 0x1000
	v_lshl_add_u64 v[78:79], v[64:65], 0, s[36:37]
	v_pk_mul_f32 v[96:97], v[68:69], v[96:97] op_sel_hi:[0,1]
	v_pk_mul_f32 v[98:99], v[68:69], v[98:99] op_sel_hi:[0,1]
	v_pk_fma_f32 v[60:61], v[66:67], v[60:61], v[96:97] op_sel_hi:[0,1,1]
	v_pk_fma_f32 v[62:63], v[66:67], v[62:63], v[98:99] op_sel_hi:[0,1,1]
	v_cvt_pk_bf16_f32 v60, v60, v61
	v_cvt_pk_bf16_f32 v61, v62, v63
	ds_write_b64 v75, v[60:61]
	v_pk_mul_f32 v[100:101], v[68:69], v[100:101] op_sel_hi:[0,1]
	v_pk_mul_f32 v[102:103], v[68:69], v[102:103] op_sel_hi:[0,1]
	v_pk_fma_f32 v[56:57], v[66:67], v[56:57], v[100:101] op_sel_hi:[0,1,1]
	v_pk_fma_f32 v[58:59], v[66:67], v[58:59], v[102:103] op_sel_hi:[0,1,1]
	v_cvt_pk_bf16_f32 v56, v56, v57
	v_cvt_pk_bf16_f32 v57, v58, v59
	ds_write_b64 v75, v[56:57] offset:32
	v_pk_mul_f32 v[104:105], v[68:69], v[104:105] op_sel_hi:[0,1]
	v_pk_mul_f32 v[106:107], v[68:69], v[106:107] op_sel_hi:[0,1]
	v_pk_fma_f32 v[52:53], v[66:67], v[52:53], v[104:105] op_sel_hi:[0,1,1]
	v_pk_fma_f32 v[54:55], v[66:67], v[54:55], v[106:107] op_sel_hi:[0,1,1]
	v_cvt_pk_bf16_f32 v52, v52, v53
	v_cvt_pk_bf16_f32 v53, v54, v55
	ds_write_b64 v75, v[52:53] offset:64
	v_pk_mul_f32 v[108:109], v[68:69], v[108:109] op_sel_hi:[0,1]
	v_pk_mul_f32 v[110:111], v[68:69], v[110:111] op_sel_hi:[0,1]
	v_pk_fma_f32 v[48:49], v[66:67], v[48:49], v[108:109] op_sel_hi:[0,1,1]
	v_pk_fma_f32 v[50:51], v[66:67], v[50:51], v[110:111] op_sel_hi:[0,1,1]
	v_cvt_pk_bf16_f32 v48, v48, v49
	v_cvt_pk_bf16_f32 v49, v50, v51
	ds_write_b64 v75, v[48:49] offset:96
	v_pk_mul_f32 v[112:113], v[68:69], v[112:113] op_sel_hi:[0,1]
	v_pk_mul_f32 v[114:115], v[68:69], v[114:115] op_sel_hi:[0,1]
	v_pk_fma_f32 v[44:45], v[66:67], v[44:45], v[112:113] op_sel_hi:[0,1,1]
	v_pk_fma_f32 v[46:47], v[66:67], v[46:47], v[114:115] op_sel_hi:[0,1,1]
	v_cvt_pk_bf16_f32 v44, v44, v45
	v_cvt_pk_bf16_f32 v45, v46, v47
	ds_write_b64 v75, v[44:45] offset:128
	v_pk_mul_f32 v[116:117], v[68:69], v[116:117] op_sel_hi:[0,1]
	v_pk_mul_f32 v[118:119], v[68:69], v[118:119] op_sel_hi:[0,1]
	v_pk_fma_f32 v[40:41], v[66:67], v[40:41], v[116:117] op_sel_hi:[0,1,1]
	v_pk_fma_f32 v[42:43], v[66:67], v[42:43], v[118:119] op_sel_hi:[0,1,1]
	v_cvt_pk_bf16_f32 v40, v40, v41
	v_cvt_pk_bf16_f32 v41, v42, v43
	ds_write_b64 v75, v[40:41] offset:160
	v_pk_mul_f32 v[120:121], v[68:69], v[120:121] op_sel_hi:[0,1]
	v_pk_mul_f32 v[122:123], v[68:69], v[122:123] op_sel_hi:[0,1]
	v_pk_fma_f32 v[36:37], v[66:67], v[36:37], v[120:121] op_sel_hi:[0,1,1]
	v_pk_fma_f32 v[38:39], v[66:67], v[38:39], v[122:123] op_sel_hi:[0,1,1]
	v_cvt_pk_bf16_f32 v36, v36, v37
	v_cvt_pk_bf16_f32 v37, v38, v39
	ds_write_b64 v75, v[36:37] offset:192
	v_pk_mul_f32 v[124:125], v[68:69], v[124:125] op_sel_hi:[0,1]
	v_pk_mul_f32 v[126:127], v[68:69], v[126:127] op_sel_hi:[0,1]
	v_pk_fma_f32 v[32:33], v[66:67], v[32:33], v[124:125] op_sel_hi:[0,1,1]
	v_pk_fma_f32 v[34:35], v[66:67], v[34:35], v[126:127] op_sel_hi:[0,1,1]
	v_cvt_pk_bf16_f32 v32, v32, v33
	v_cvt_pk_bf16_f32 v33, v34, v35
	ds_write_b64 v75, v[32:33] offset:224
	v_pk_mul_f32 v[128:129], v[68:69], v[128:129] op_sel_hi:[0,1]
	v_pk_mul_f32 v[130:131], v[68:69], v[130:131] op_sel_hi:[0,1]
	v_pk_fma_f32 v[28:29], v[66:67], v[28:29], v[128:129] op_sel_hi:[0,1,1]
	v_pk_fma_f32 v[30:31], v[66:67], v[30:31], v[130:131] op_sel_hi:[0,1,1]
	v_cvt_pk_bf16_f32 v28, v28, v29
	v_cvt_pk_bf16_f32 v29, v30, v31
	ds_write_b64 v75, v[28:29] offset:256
	v_pk_mul_f32 v[132:133], v[68:69], v[132:133] op_sel_hi:[0,1]
	v_pk_mul_f32 v[134:135], v[68:69], v[134:135] op_sel_hi:[0,1]
	v_pk_fma_f32 v[24:25], v[66:67], v[24:25], v[132:133] op_sel_hi:[0,1,1]
	v_pk_fma_f32 v[26:27], v[66:67], v[26:27], v[134:135] op_sel_hi:[0,1,1]
	v_cvt_pk_bf16_f32 v24, v24, v25
	v_cvt_pk_bf16_f32 v25, v26, v27
	ds_write_b64 v75, v[24:25] offset:288
	v_pk_mul_f32 v[136:137], v[68:69], v[136:137] op_sel_hi:[0,1]
	v_pk_mul_f32 v[138:139], v[68:69], v[138:139] op_sel_hi:[0,1]
	v_pk_fma_f32 v[20:21], v[66:67], v[20:21], v[136:137] op_sel_hi:[0,1,1]
	v_pk_fma_f32 v[22:23], v[66:67], v[22:23], v[138:139] op_sel_hi:[0,1,1]
	v_cvt_pk_bf16_f32 v20, v20, v21
	v_cvt_pk_bf16_f32 v21, v22, v23
	ds_write_b64 v75, v[20:21] offset:320
	v_pk_mul_f32 v[140:141], v[68:69], v[140:141] op_sel_hi:[0,1]
	v_pk_mul_f32 v[142:143], v[68:69], v[142:143] op_sel_hi:[0,1]
	v_pk_fma_f32 v[16:17], v[66:67], v[16:17], v[140:141] op_sel_hi:[0,1,1]
	v_pk_fma_f32 v[18:19], v[66:67], v[18:19], v[142:143] op_sel_hi:[0,1,1]
	v_cvt_pk_bf16_f32 v16, v16, v17
	v_cvt_pk_bf16_f32 v17, v18, v19
	ds_write_b64 v75, v[16:17] offset:352
	v_pk_mul_f32 v[144:145], v[68:69], v[144:145] op_sel_hi:[0,1]
	v_pk_mul_f32 v[146:147], v[68:69], v[146:147] op_sel_hi:[0,1]
	v_pk_fma_f32 v[12:13], v[66:67], v[12:13], v[144:145] op_sel_hi:[0,1,1]
	v_pk_fma_f32 v[14:15], v[66:67], v[14:15], v[146:147] op_sel_hi:[0,1,1]
	v_cvt_pk_bf16_f32 v12, v12, v13
	v_cvt_pk_bf16_f32 v13, v14, v15
	ds_write_b64 v75, v[12:13] offset:384
	v_pk_mul_f32 v[148:149], v[68:69], v[148:149] op_sel_hi:[0,1]
	v_pk_mul_f32 v[150:151], v[68:69], v[150:151] op_sel_hi:[0,1]
	v_pk_fma_f32 v[8:9], v[66:67], v[8:9], v[148:149] op_sel_hi:[0,1,1]
	v_pk_fma_f32 v[10:11], v[66:67], v[10:11], v[150:151] op_sel_hi:[0,1,1]
	v_cvt_pk_bf16_f32 v8, v8, v9
	v_cvt_pk_bf16_f32 v9, v10, v11
	ds_write_b64 v75, v[8:9] offset:416
	v_pk_mul_f32 v[152:153], v[68:69], v[152:153] op_sel_hi:[0,1]
	v_pk_mul_f32 v[154:155], v[68:69], v[154:155] op_sel_hi:[0,1]
	v_pk_fma_f32 v[4:5], v[66:67], v[4:5], v[152:153] op_sel_hi:[0,1,1]
	v_pk_fma_f32 v[6:7], v[66:67], v[6:7], v[154:155] op_sel_hi:[0,1,1]
	v_cvt_pk_bf16_f32 v4, v4, v5
	v_cvt_pk_bf16_f32 v5, v6, v7
	ds_write_b64 v75, v[4:5] offset:448
	v_pk_mul_f32 v[156:157], v[68:69], v[156:157] op_sel_hi:[0,1]
	v_pk_mul_f32 v[158:159], v[68:69], v[158:159] op_sel_hi:[0,1]
	v_pk_fma_f32 v[0:1], v[66:67], v[0:1], v[156:157] op_sel_hi:[0,1,1]
	v_pk_fma_f32 v[2:3], v[66:67], v[2:3], v[158:159] op_sel_hi:[0,1,1]
	v_cvt_pk_bf16_f32 v0, v0, v1
	v_cvt_pk_bf16_f32 v1, v2, v3
	ds_write_b64 v75, v[0:1] offset:480
	s_waitcnt lgkmcnt(0)
	ds_read_b128 v[96:99], v76
	ds_read_b128 v[100:103], v76 offset:1056
	ds_read_b128 v[104:107], v76 offset:2112
	ds_read_b128 v[108:111], v76 offset:3168
	ds_read_b128 v[112:115], v76 offset:4224
	ds_read_b128 v[116:119], v76 offset:5280
	ds_read_b128 v[120:123], v76 offset:6336
	ds_read_b128 v[124:127], v76 offset:7392
	s_waitcnt lgkmcnt(7)
	global_store_dwordx4 v[64:65], v[96:99], off
	s_waitcnt lgkmcnt(6)
	global_store_dwordx4 v[64:65], v[100:103], off offset:1024
	s_waitcnt lgkmcnt(5)
	global_store_dwordx4 v[64:65], v[104:107], off offset:2048
	s_waitcnt lgkmcnt(4)
	global_store_dwordx4 v[64:65], v[108:111], off offset:3072
	s_waitcnt lgkmcnt(3)
	global_store_dwordx4 v[78:79], v[112:115], off
	s_waitcnt lgkmcnt(2)
	global_store_dwordx4 v[78:79], v[116:119], off offset:1024
	s_waitcnt lgkmcnt(1)
	global_store_dwordx4 v[78:79], v[120:123], off offset:2048
	s_waitcnt lgkmcnt(0)
	global_store_dwordx4 v[78:79], v[124:127], off offset:3072
